# P3-head deferred w_out0 transposes also moved to even-numbered workgroups (with the P6-head block)
# speedup vs baseline: 1.0026x; 1.0026x over previous
.LBB0_386:
	s_or_b64 exec, exec, s[0:1]
	s_bitcmp1_b32 s2, 0
	s_cbranch_scc1 .Ldf_skip_p3
	v_writelane_b32 v234, s0, 0
	v_writelane_b32 v234, s1, 1
	v_writelane_b32 v234, s2, 2
	v_writelane_b32 v234, s3, 3
	v_writelane_b32 v234, s4, 4
	v_writelane_b32 v234, s5, 5
	v_writelane_b32 v234, s6, 6
	v_writelane_b32 v234, s7, 7
	v_writelane_b32 v234, s8, 8
	v_writelane_b32 v234, s9, 9
	v_writelane_b32 v234, s10, 10
	v_writelane_b32 v234, s11, 11
	v_writelane_b32 v234, s12, 12
	v_writelane_b32 v234, s13, 13
	v_writelane_b32 v234, s14, 14
	v_writelane_b32 v234, s15, 15
	v_writelane_b32 v234, s16, 16
	v_writelane_b32 v234, s17, 17
	v_writelane_b32 v234, s18, 18
	v_writelane_b32 v234, s19, 19
	v_writelane_b32 v234, s20, 20
	v_writelane_b32 v234, s21, 21
	v_writelane_b32 v234, s22, 22
	v_writelane_b32 v234, s23, 23
	v_writelane_b32 v234, s24, 24
	v_writelane_b32 v234, s25, 25
	v_writelane_b32 v234, s26, 26
	v_writelane_b32 v234, s27, 27
	v_writelane_b32 v234, s28, 28
	v_writelane_b32 v234, s29, 29
	v_writelane_b32 v234, s30, 30
	v_writelane_b32 v234, s31, 31
	v_writelane_b32 v234, s32, 32
	v_writelane_b32 v234, s33, 33
	v_writelane_b32 v234, s34, 34
	v_writelane_b32 v234, s35, 35
	v_writelane_b32 v234, s36, 36
	v_writelane_b32 v234, s37, 37
	v_writelane_b32 v234, s38, 38
	v_writelane_b32 v234, s39, 39
	v_writelane_b32 v234, s40, 40
	v_writelane_b32 v234, s41, 41
	v_writelane_b32 v234, s42, 42
	v_writelane_b32 v234, s43, 43
	v_writelane_b32 v234, s44, 44
	v_writelane_b32 v234, s45, 45
	v_writelane_b32 v234, s46, 46
	v_writelane_b32 v234, s47, 47
	v_writelane_b32 v234, s48, 48
	v_writelane_b32 v234, s49, 49
	v_writelane_b32 v234, s50, 50
	v_writelane_b32 v234, s51, 51
	v_writelane_b32 v234, s52, 52
	v_writelane_b32 v234, s53, 53
	v_writelane_b32 v234, s54, 54
	v_writelane_b32 v234, s55, 55
	v_writelane_b32 v234, s56, 56
	v_writelane_b32 v234, s57, 57
	v_writelane_b32 v234, s58, 58
	v_writelane_b32 v234, s59, 59
	v_writelane_b32 v234, s60, 60
	v_writelane_b32 v234, s61, 61
	v_writelane_b32 v234, s62, 62
	v_writelane_b32 v234, s63, 63
	v_writelane_b32 v235, s64, 0
	v_writelane_b32 v235, s65, 1
	v_writelane_b32 v235, s66, 2
	v_writelane_b32 v235, s67, 3
	v_writelane_b32 v235, s68, 4
	v_writelane_b32 v235, s69, 5
	v_writelane_b32 v235, s70, 6
	v_writelane_b32 v235, s71, 7
	v_writelane_b32 v235, s72, 8
	v_writelane_b32 v235, s73, 9
	v_writelane_b32 v235, s74, 10
	v_writelane_b32 v235, s75, 11
	v_writelane_b32 v235, s76, 12
	v_writelane_b32 v235, s77, 13
	v_writelane_b32 v235, s78, 14
	v_writelane_b32 v235, s79, 15
	v_writelane_b32 v235, s80, 16
	v_writelane_b32 v235, s81, 17
	v_writelane_b32 v235, s82, 18
	v_writelane_b32 v235, s83, 19
	v_writelane_b32 v235, s84, 20
	v_writelane_b32 v235, s85, 21
	v_writelane_b32 v235, s86, 22
	v_writelane_b32 v235, s87, 23
	v_writelane_b32 v235, s88, 24
	v_writelane_b32 v235, s89, 25
	v_writelane_b32 v235, s90, 26
	v_writelane_b32 v235, s91, 27
	v_writelane_b32 v235, s92, 28
	v_writelane_b32 v235, s93, 29
	v_writelane_b32 v235, s94, 30
	v_writelane_b32 v235, s95, 31
	v_writelane_b32 v235, s96, 32
	v_writelane_b32 v235, s97, 33
	v_writelane_b32 v235, vcc_lo, 34
	v_writelane_b32 v235, vcc_hi, 35
	v_readlane_b32 s72, v233, 47
	v_readlane_b32 s73, v233, 48
	v_readlane_b32 s74, v233, 49
	v_readlane_b32 s75, v233, 50
	v_readlane_b32 s76, v233, 51
	v_readlane_b32 s77, v233, 52
	s_add_u32 s62, s92, 0x400000
	s_addc_u32 s63, s93, 0
	v_mov_b32_e32 v1, v210
	s_nop 0
	v_readfirstlane_b32 s0, v1
	v_and_b32_e32 v76, 63, v1
	s_nop 3
	s_ashr_i32 s8, s0, 6
	s_lshr_b32 s1, s2, 1
	s_lshl_b32 s1, s1, 0
	s_and_b32 s3, s2, 0
	s_or_b32 s1, s1, s3
	s_lshl_b32 s1, s1, 3
	s_add_i32 s26, s8, s1
	s_addk_i32 s26, 0x1c80
	s_movk_i32 s96, 0x400
	s_movk_i32 s101, 0x247f
	s_mov_b32 s100, 2
	s_branch .Lp0_setup
